# combined: attention loop cleanups + early K/V DMA issue + de-serialised gated-residual epilogues + batched merge transposition loads
# speedup vs baseline: 1.0123x; 1.0074x over previous
; #define YH ((float*)(wsb(a.ws) + WS_YH))
; #define YHC ((float*)(wsb(a.ws) + WS_YHC))
; __global__ void __launch_bounds__(NTHR, 2) fwd_mega(Args a) {
;     ...
;             for (int tl = bx; tl < ntile; tl += G) {
;                 const int r0 = tl * 64; const float* yb; int cstride;
;                 if (r0 < ML) { yb = YH + (size_t)(r0 >> 13) * 256 * 8192 + (r0 & 8191); cstride = 8192; } else { const int rr = r0 - ML; yb = YHC + (size_t)(rr >> 8) * 256 * 256 + (rr & 255); cstride = 256; }
;                 for (int i = 0; i < 32; ++i) { const int c = i * 8 + wave; S[lane * 257 + c] = yb[(size_t)c * cstride + lane]; }
;                 __syncthreads();
.LBB0_851:
	v_lshl_add_u64 v[10:11], s[12:13], 0, v[2:3]
	global_load_dword v9, v[10:11], off
	v_add_u32_e32 v15, s36, v13
	v_lshl_add_u64 v[10:11], s[14:15], 0, v[2:3]
	s_addk_i32 s36, 0x80
	global_load_dword v16, v[10:11], off
	v_lshl_add_u64 v[10:11], s[10:11], 0, v[2:3]
	global_load_dword v17, v[10:11], off
	v_lshl_add_u64 v[10:11], s[6:7], 0, v[2:3]
	s_add_u32 s6, s6, s37
	s_addc_u32 s7, s7, 0
	s_add_u32 s10, s10, s37
	s_addc_u32 s11, s11, 0
	s_add_u32 s14, s14, s37
	s_addc_u32 s15, s15, 0
	s_add_u32 s12, s12, s37
	s_addc_u32 s13, s13, 0
	global_load_dword v18, v[10:11], off
	s_cmpk_eq_i32 s36, 0x400
	s_waitcnt vmcnt(3) lgkmcnt(0)
	ds_write_b32 v15, v9
	s_waitcnt vmcnt(2)
	ds_write_b32 v15, v16 offset:32
	s_waitcnt vmcnt(1)
	ds_write_b32 v15, v17 offset:64
	s_waitcnt vmcnt(0)
	ds_write_b32 v15, v18 offset:96
	s_cbranch_scc0 .LBB0_851
	s_mov_b32 s14, 0
	s_mov_b32 s6, s35
	s_waitcnt lgkmcnt(0)
	s_barrier
